# v30 + blocks>=128 start the G1 and G3 GEMM phases 1x s_sleep127 late (store bursts of the two tile groups per XCD de-phased)
# speedup vs baseline: 1.0005x; 1.0001x over previous
;     __device__ void init(int N, int G, int c) { S.init(NBATCH * SEQ, N, G, c); }
; __global__ void __launch_bounds__(512, 2) hybrid_fwd(Params Parg) {
;     ...
;         xcd_barrier(bar);
;         for (int rep = 0; rep < REP_G1; ++rep) {
;         { const Params P = fresh_params(); const int G = gridDim.x, blk = blockIdx.x;
;           pg8::Gemm g{(const pg8::bf16_t*)(P.ws + WS_H), (const pg8::bf16_t*)(P.ws + (size_t)(l & 1) * WS_WBUF + WS_W), ROWS, INW, DM}; pg8::StaticOrder S; S.init(ROWS, INW, G, blk);
;           pg8::EpiBf16<0> E{(pg8::bf16_t*)(P.ws + WS_PROJ), INW, nullptr, 0, 0, 1.0f};
;           pg8::gemm_phase<pg8::EpiBf16<0>, pg8::StaticOrder, true, true>(ldsl, g, S, E); }
.LBB0_157:
	s_or_b64 exec, exec, s[0:1]
	v_readlane_b32 s0, v255, 0
	v_readlane_b32 s1, v255, 1
	v_readlane_b32 s8, v253, 46
	s_bitcmp1_b32 s0, 0
	s_mov_b64 s[0:1], s[28:29]
	v_mov_b32_e32 v8, v200
	v_readlane_b32 s9, v253, 47
	s_waitcnt lgkmcnt(0)
	s_barrier
	s_cselect_b32 s70, 0x1800000, 0
	s_cmp_lt_u32 s2, 128
	s_cbranch_scc1 .Lg1st_go
	s_mov_b32 s100, 1

; #define PG8_STAGE(bufoff, gbase, voff) do { _Pragma("unroll") for (int _i = 0; _i < 2; ++_i) \
;         __builtin_amdgcn_global_load_lds((const unsigned*)((const char*)(gbase) + (voff)[_i]), (PG8_LAS unsigned*)(lds + (bufoff) + ldsw + _i * 8192), 16, 0, 0); } while (0)
; #define PG8_BAR __builtin_amdgcn_s_barrier()
; template <class Epi, class Sched, bool ALIGN_EPI = false, bool SP2 = false>
; __device__ __forceinline__ void gemm_phase(PG8_LAS unsigned char* lds, const Gemm g, const Sched& S, const Epi& E) {
;     ...
;     const int tid = tid_o, wid = __builtin_amdgcn_readfirstlane(tid >> 6), lane = tid & 63, wr = wid >> 2, wc = wid & 3, fr = lane & 15, fq = lane >> 4;
;     const int K = g.K, nt = K / BK;
;     unsigned voffA[2], voffB[2];
; #pragma unroll
;     for (int i = 0; i < 2; ++i) { int R, C; stage_rc(tid * 16 + i * 8192, R, C); const int Rb = Epi::PERM ? ((R & ~31) + perm32(R & 31)) : R;
;         voffA[i] = (unsigned)(R * K + C) * 2u; voffB[i] = (unsigned)(Rb * K + C) * 2u; }
;     const size_t kstep = (size_t)(BK * 2);
;     const size_t hstep = (size_t)HALF * K * 2;
;     const size_t tstep = 2 * hstep;
;     const unsigned ldsw = (unsigned)wid * 1024u;
;     const int aoff = lds_byte(wr * 64 + fr, fq * 8), boff = lds_byte(wc * 32 + fr, fq * 8);
;     ...
;     const char* cA = (const char*)g.A + (size_t)cur.pm * tstep; const char* cB = (const char*)g.Bt + (size_t)cur.pn * tstep;
;     S.a_ready(cur);
;     if constexpr (SP2) {
;         PG8_STAGE(PG8_SB(0, 0), cB, voffB); PG8_STAGE(PG8_SB(0, 1), cB + hstep, voffB); PG8_STAGE(PG8_SA(0, 0), cA, voffA); PG8_STAGE(PG8_SA(0, 1), cA + hstep, voffA);
;         if (wr == 1) PG8_BAR;
.Lg1st_go:
	s_and_b64 vcc, exec, s[8:9]
	v_readfirstlane_b32 s12, v8
	s_cbranch_vccz .LBB0_173
	v_lshlrev_b32_e32 v0, 4, v8
	v_add_u32_e32 v1, 0x2000, v0
	v_ashrrev_i32_e32 v2, 31, v1
	v_lshrrev_b32_e32 v2, 22, v2
	v_add_u32_e32 v2, v1, v2
	v_ashrrev_i32_e32 v9, 10, v2
	s_load_dwordx2 s[10:11], s[0:1], 0xa0
	v_mul_i32_i24_e32 v2, 0x400, v9
	v_sub_u32_e32 v1, v1, v2
	v_lshrrev_b32_e32 v2, 4, v1
	v_bitop3_b32 v1, v2, v1, 32 bitop3:0x6c
	v_ashrrev_i32_e32 v2, 31, v1
	s_waitcnt lgkmcnt(0)
	s_add_u32 s8, s10, 0x5500000
	v_lshrrev_b32_e32 v2, 26, v2
	s_addc_u32 s9, s11, 0
	v_add_u32_e32 v2, v1, v2
	v_lshlrev_b32_e32 v3, 3, v9
	s_add_u32 s0, s10, s70
	v_ashrrev_i32_e32 v10, 6, v2
	v_and_b32_e32 v3, -16, v3
	s_addc_u32 s1, s11, 0
	v_add_u32_e32 v3, v10, v3
	s_add_u32 s15, s0, 0x400000
	v_and_b32_e32 v4, 3, v10
	s_mov_b32 s0, 0x1fffe0
	v_lshrrev_b32_e32 v5, 2, v3
	v_lshlrev_b32_e32 v6, 1, v3
	v_and_b32_e32 v2, 0xc0, v2
	v_and_or_b32 v4, v3, s0, v4
	v_and_b32_e32 v5, 4, v5
	v_and_b32_e32 v6, 24, v6
	v_sub_u32_e32 v1, v1, v2
	v_or3_b32 v4, v4, v5, v6
	v_lshlrev_b32_e32 v5, 5, v9
	v_ashrrev_i16_sdwa v1, v203, sext(v1) dst_sel:DWORD dst_unused:UNUSED_PAD src0_sel:DWORD src1_sel:BYTE_0
	v_and_b32_e32 v5, 32, v5
	v_bfe_i32 v11, v1, 0, 16
	v_add_lshl_u32 v1, v5, v11, 1
	v_lshl_add_u32 v130, v4, 11, v1
	v_lshl_add_u32 v132, v3, 11, v1
	v_bfe_i32 v1, v8, 27, 1
	v_lshrrev_b32_e32 v1, 22, v1
	v_add_u32_e32 v1, v0, v1
	v_and_b32_e32 v1, 0xfffffc00, v1
	v_sub_u32_e32 v0, v0, v1
	v_lshrrev_b32_e32 v1, 4, v0
	v_ashrrev_i32_e32 v2, 31, v8
	v_bitop3_b32 v0, v1, v0, 32 bitop3:0x6c
	v_lshrrev_b32_e32 v2, 26, v2
	v_ashrrev_i32_e32 v1, 31, v0
	v_add_u32_e32 v2, v8, v2
	v_lshrrev_b32_e32 v1, 26, v1
	v_ashrrev_i32_e32 v13, 6, v2
	v_add_u32_e32 v1, v0, v1
	v_lshlrev_b32_e32 v2, 3, v13
	v_ashrrev_i32_e32 v12, 6, v1
	v_and_b32_e32 v2, -16, v2
	v_add_u32_e32 v2, v12, v2
	v_and_b32_e32 v3, 3, v12
	v_lshrrev_b32_e32 v4, 2, v2
	v_lshlrev_b32_e32 v5, 1, v2
	v_and_b32_e32 v1, 0xc0, v1
	s_addc_u32 s18, s1, 0
	s_ashr_i32 s24, s12, 6
	v_and_or_b32 v3, v2, s0, v3
	v_and_b32_e32 v4, 4, v4
	v_and_b32_e32 v5, 24, v5
	v_sub_u32_e32 v0, v0, v1
	s_ashr_i32 s13, s12, 8
	s_lshl_b32 s19, s24, 10
	v_or3_b32 v3, v3, v4, v5
	v_lshlrev_b32_e32 v4, 5, v13
	v_ashrrev_i16_sdwa v0, v203, sext(v0) dst_sel:DWORD dst_unused:UNUSED_PAD src0_sel:DWORD src1_sel:BYTE_0
	v_readlane_b32 s0, v254, 2
	v_and_b32_e32 v4, 32, v4
	v_bfe_i32 v14, v0, 0, 16
	v_readlane_b32 s1, v254, 3
	s_add_u32 s48, s15, s0
	v_add_lshl_u32 v0, v4, v14, 1
	s_addc_u32 s49, s18, s1
	s_add_i32 s28, s19, 0
	v_lshl_add_u32 v128, v3, 11, v0
	s_add_i32 m0, s28, 0x10000
	v_lshl_add_u32 v134, v2, 11, v0
	global_load_lds_dwordx4 v128, s[48:49]
	s_add_i32 m0, s28, 0x12000
	s_add_u32 s0, s48, 0x40000
	global_load_lds_dwordx4 v130, s[48:49]
	s_addc_u32 s1, s49, 0
	s_add_i32 m0, s28, 0x14000
	v_mov_b32_e32 v131, v129
	global_load_lds_dwordx4 v128, s[0:1]
	s_add_i32 m0, s28, 0x16000
	v_mov_b32_e32 v135, v129
	global_load_lds_dwordx4 v130, s[0:1]
	v_readlane_b32 s0, v254, 29
	v_readlane_b32 s1, v254, 30
	s_add_u32 s46, s8, s0
	s_addc_u32 s47, s9, s1
	s_add_i32 s29, s28, 0x2000
	s_mov_b32 m0, s28
	s_add_u32 s0, s46, 0x40000
	global_load_lds_dwordx4 v134, s[46:47]
	s_mov_b32 m0, s29
	s_addc_u32 s1, s47, 0
	s_add_i32 s52, s28, 0x4000
	global_load_lds_dwordx4 v132, s[46:47]
	s_mov_b32 m0, s52
	s_add_i32 s53, s28, 0x6000
	global_load_lds_dwordx4 v134, s[0:1]
	s_mov_b32 m0, s53
	v_mov_b32_e32 v133, v129
	global_load_lds_dwordx4 v132, s[0:1]
	s_cmp_eq_u32 s13, 1
	v_lshl_add_u64 v[6:7], s[48:49], 0, v[128:129]
	v_lshl_add_u64 v[4:5], s[48:49], 0, v[130:131]
	v_lshl_add_u64 v[0:1], s[46:47], 0, v[134:135]
	s_cselect_b64 s[0:1], -1, 0
	s_cmp_lg_u32 s13, 1
	v_lshl_add_u64 v[2:3], s[46:47], 0, v[132:133]
	s_cbranch_scc1 .LBB0_160
	s_barrier

;     __device__ void init(int N, int G, int c) { S.init(NBATCH * SEQ, N, G, c); }
; __global__ void __launch_bounds__(512, 2) hybrid_fwd(Params Parg) {
;     ...
;         { const Params P = fresh_params(); const int G = gridDim.x, blk = blockIdx.x;
;           pg8::Gemm g{(const pg8::bf16_t*)(P.ws + WS_H), (const pg8::bf16_t*)(P.ws + (size_t)(l & 1) * WS_WBUF + WS_W_FI), ROWS, 2 * FFH, DM};
;           EpiSwiGLU E{(bf16_t*)(P.ws + WS_PROJ)};
;           if (lat_only) { LatOrder S; S.init(2 * FFH, G, blk); pg8::gemm_phase<EpiSwiGLU, LatOrder, true, true>(ldsl, g, S, E); }
;           else { pg8::StaticOrder S; S.init(ROWS, 2 * FFH, G, blk); pg8::gemm_phase<EpiSwiGLU, pg8::StaticOrder, true, true>(ldsl, g, S, E); } }
.LBB0_992:
	s_or_b64 exec, exec, s[10:11]
	s_mov_b64 s[0:1], s[18:19]
	s_waitcnt lgkmcnt(0)
	s_barrier
	s_cmp_lt_u32 s2, 128
	s_cbranch_scc1 .Lg3st_go
	s_mov_b32 s100, 1

;     __device__ void init(int N, int G, int c) { S.init(NBATCH * SEQ, N, G, c); }
; template <class Epi, class Sched, bool ALIGN_EPI = false, bool SP2 = false>
; __device__ __forceinline__ void gemm_phase(PG8_LAS unsigned char* lds, const Gemm g, const Sched& S, const Epi& E) {
;     ...
;     const int tid = tid_o, wid = __builtin_amdgcn_readfirstlane(tid >> 6), lane = tid & 63, wr = wid >> 2, wc = wid & 3, fr = lane & 15, fq = lane >> 4;
;     const int K = g.K, nt = K / BK;
;     unsigned voffA[2], voffB[2];
; #pragma unroll
;     for (int i = 0; i < 2; ++i) { int R, C; stage_rc(tid * 16 + i * 8192, R, C); const int Rb = Epi::PERM ? ((R & ~31) + perm32(R & 31)) : R;
;         voffA[i] = (unsigned)(R * K + C) * 2u; voffB[i] = (unsigned)(Rb * K + C) * 2u; }
;     const size_t kstep = (size_t)(BK * 2);
;     const size_t hstep = (size_t)HALF * K * 2;
;     const size_t tstep = 2 * hstep;
;     const unsigned ldsw = (unsigned)wid * 1024u;
;     const int aoff = lds_byte(wr * 64 + fr, fq * 8), boff = lds_byte(wc * 32 + fr, fq * 8);
; __global__ void __launch_bounds__(512, 2) hybrid_fwd(Params Parg) {
;     ...
;         { const Params P = fresh_params(); const int G = gridDim.x, blk = blockIdx.x;
;           pg8::Gemm g{(const pg8::bf16_t*)(P.ws + WS_H), (const pg8::bf16_t*)(P.ws + (size_t)(l & 1) * WS_WBUF + WS_W_FI), ROWS, 2 * FFH, DM};
;           EpiSwiGLU E{(bf16_t*)(P.ws + WS_PROJ)};
;           if (lat_only) { LatOrder S; S.init(2 * FFH, G, blk); pg8::gemm_phase<EpiSwiGLU, LatOrder, true, true>(ldsl, g, S, E); }
;           else { pg8::StaticOrder S; S.init(ROWS, 2 * FFH, G, blk); pg8::gemm_phase<EpiSwiGLU, pg8::StaticOrder, true, true>(ldsl, g, S, E); } }
.Lg3st_go:
	s_load_dwordx2 s[10:11], s[0:1], 0xa0
	v_readlane_b32 s12, v255, 3
	v_readlane_b32 s13, v255, 4
	s_mov_b64 s[24:25], -1
	s_waitcnt lgkmcnt(0)
	s_add_u32 s0, s10, 0x5500000
	s_addc_u32 s1, s11, 0
	s_add_u32 s8, s10, s70
	s_addc_u32 s9, s11, 0
	s_add_u32 s8, s8, 0xb80000
	s_addc_u32 s9, s9, 0
	s_add_u32 s10, s10, 0x9d00000
	s_addc_u32 s11, s11, 0
	s_and_b64 vcc, exec, s[12:13]
	s_cbranch_vccz .LBB0_1010
	v_readlane_b32 s12, v253, 56
	v_mov_b32_e32 v0, v200
	v_readlane_b32 s13, v253, 57
	s_andn2_b64 vcc, exec, s[12:13]
	v_readfirstlane_b32 s12, v0
	s_cbranch_vccnz .LBB0_1009
	v_lshlrev_b32_e32 v4, 4, v0
	v_add_u32_e32 v2, 0x2000, v4
	v_ashrrev_i32_e32 v1, 31, v2
	v_lshrrev_b32_e32 v1, 22, v1
	v_add_u32_e32 v1, v2, v1
	v_ashrrev_i32_e32 v1, 10, v1
	v_mul_i32_i24_e32 v3, 0x400, v1
	v_sub_u32_e32 v2, v2, v3
	v_lshrrev_b32_e32 v3, 4, v2
	v_bitop3_b32 v3, v3, v2, 32 bitop3:0x6c
	v_ashrrev_i32_e32 v2, 31, v3
	v_lshrrev_b32_e32 v2, 26, v2
	v_add_u32_e32 v5, v3, v2
	v_lshlrev_b32_e32 v6, 3, v1
	v_ashrrev_i32_e32 v2, 6, v5
	v_and_b32_e32 v6, -16, v6
	v_add_u32_e32 v6, v2, v6
	v_and_b32_e32 v7, 3, v2
	s_mov_b32 s6, 0x1fffe0
	s_waitcnt vmcnt(2)
	v_lshrrev_b32_e32 v8, 2, v6
	v_lshlrev_b32_e32 v9, 1, v6
	v_and_b32_e32 v5, 0xc0, v5
	v_and_or_b32 v7, v6, s6, v7
	v_and_b32_e32 v8, 4, v8
	v_and_b32_e32 v9, 24, v9
	v_sub_u32_e32 v3, v3, v5
	v_or3_b32 v7, v7, v8, v9
	v_lshlrev_b32_e32 v8, 5, v1
	v_ashrrev_i16_sdwa v3, v203, sext(v3) dst_sel:DWORD dst_unused:UNUSED_PAD src0_sel:DWORD src1_sel:BYTE_0
	v_and_b32_e32 v8, 32, v8
	v_bfe_i32 v3, v3, 0, 16
	v_add_lshl_u32 v5, v8, v3, 1
	v_lshl_add_u32 v130, v7, 11, v5
	v_lshl_add_u32 v132, v6, 11, v5
	v_bfe_i32 v5, v0, 27, 1
	v_lshrrev_b32_e32 v5, 22, v5
	v_add_u32_e32 v5, v4, v5
	v_and_b32_e32 v5, 0xfffffc00, v5
	v_sub_u32_e32 v4, v4, v5
	v_lshrrev_b32_e32 v5, 4, v4
	v_bitop3_b32 v6, v5, v4, 32 bitop3:0x6c
	v_ashrrev_i32_e32 v5, 31, v0
	v_lshrrev_b32_e32 v5, 26, v5
	v_ashrrev_i32_e32 v4, 31, v6
	v_add_u32_e32 v5, v0, v5
	v_lshrrev_b32_e32 v4, 26, v4
	v_ashrrev_i32_e32 v5, 6, v5
	v_add_u32_e32 v7, v6, v4
	v_lshlrev_b32_e32 v8, 3, v5
	v_ashrrev_i32_e32 v4, 6, v7
	v_and_b32_e32 v8, -16, v8
	v_add_u32_e32 v8, v4, v8
	v_and_b32_e32 v9, 3, v4
	v_lshrrev_b32_e32 v10, 2, v8
	v_lshlrev_b32_e32 v11, 1, v8
	v_and_b32_e32 v7, 0xc0, v7
	s_ashr_i32 s34, s12, 6
	v_and_or_b32 v9, v8, s6, v9
	v_and_b32_e32 v10, 4, v10
	v_and_b32_e32 v11, 24, v11
	v_sub_u32_e32 v6, v6, v7
	s_ashr_i32 s13, s12, 8
	s_lshl_b32 s15, s34, 10
	v_or3_b32 v9, v9, v10, v11
	v_lshlrev_b32_e32 v10, 5, v5
	v_ashrrev_i16_sdwa v6, v203, sext(v6) dst_sel:DWORD dst_unused:UNUSED_PAD src0_sel:DWORD src1_sel:BYTE_0
	v_readlane_b32 s18, v254, 11
	v_and_b32_e32 v10, 32, v10
	v_bfe_i32 v6, v6, 0, 16
	v_readlane_b32 s19, v254, 12
	s_add_u32 s54, s8, s18
	v_add_lshl_u32 v7, v10, v6, 1
	s_addc_u32 s55, s9, s19
	s_add_i32 s18, s15, 0
	v_lshl_add_u32 v128, v9, 11, v7
	s_add_i32 m0, s18, 0x10000
	v_lshl_add_u32 v134, v8, 11, v7
	global_load_lds_dwordx4 v128, s[54:55]
	s_add_i32 m0, s18, 0x12000
	s_add_u32 s24, s54, 0x40000
	global_load_lds_dwordx4 v130, s[54:55]
	s_addc_u32 s25, s55, 0
	s_add_i32 m0, s18, 0x14000
	s_nop 0
	global_load_lds_dwordx4 v128, s[24:25]
	s_add_i32 m0, s18, 0x16000
	s_nop 0
	global_load_lds_dwordx4 v130, s[24:25]
	v_readlane_b32 s24, v254, 41
	v_readlane_b32 s25, v254, 42
	s_add_u32 s52, s0, s24
	s_addc_u32 s53, s1, s25
	s_add_i32 s19, s18, 0x2000
	s_mov_b32 m0, s18
	s_add_u32 s24, s52, 0x40000
	global_load_lds_dwordx4 v134, s[52:53]
	s_mov_b32 m0, s19
	s_addc_u32 s25, s53, 0
	s_add_i32 s28, s18, 0x4000
	global_load_lds_dwordx4 v132, s[52:53]
	s_mov_b32 m0, s28
	s_add_i32 s29, s18, 0x6000
	global_load_lds_dwordx4 v134, s[24:25]
	s_mov_b32 m0, s29
	s_cmp_eq_u32 s13, 1
	global_load_lds_dwordx4 v132, s[24:25]
	s_cselect_b64 s[24:25], -1, 0
	s_cmp_lg_u32 s13, 1
	s_cbranch_scc1 .LBB0_996
	s_barrier
